# QKV epilogue: remaining 6 adjacent scalar f32 multiply pairs merged into v_pk_mul_f32 (same f32 math)
# speedup vs baseline: 1.0156x; 1.0156x over previous
.LBB0_727:
	v_lshl_add_u32 v140, s58, 8, v135
	v_ashrrev_i32_e32 v141, 31, v140
	v_lshl_add_u64 v[142:143], v[140:141], 3, s[24:25]
	global_load_dwordx2 v[144:145], v[142:143], off
	global_load_dwordx2 v[174:175], v[142:143], off offset:128
	global_load_dwordx2 v[172:173], v[142:143], off offset:256
	global_load_dwordx2 v[152:153], v[142:143], off offset:384
	global_load_dwordx2 v[150:151], v[142:143], off offset:1024
	global_load_dwordx2 v[148:149], v[142:143], off offset:1152
	global_load_dwordx2 v[146:147], v[142:143], off offset:1280
	s_nop 0
	global_load_dwordx2 v[142:143], v[142:143], off offset:1408
	s_ashr_i32 s31, s42, 3
	s_cmp_lt_u32 s42, 8
	v_and_b32_e32 v8, 0x7cf, v140
	s_cselect_b64 vcc, -1, 0
	s_cmp_lt_i32 s31, 2
	s_flbit_i32_b32 s16, 0
	v_cvt_f32_u32_e32 v194, v8
	s_cselect_b64 s[4:5], -1, 0
	s_min_u32 s36, s16, 32
	s_sub_i32 s35, 32, s36
	v_cndmask_b32_e32 v141, 1.0, v187, vcc
	s_and_b64 s[4:5], s[28:29], s[4:5]
	v_pk_mul_f32 v[154:155], v[180:181], v[194:195] op_sel_hi:[1,0]
	v_mul_f32_e32 v156, v190, v194
	s_and_b64 vcc, exec, s[4:5]
	v_floor_f32_e32 v196, v154
	v_floor_f32_e32 v197, v155
	v_floor_f32_e32 v195, v156
	s_waitcnt vmcnt(0)
	v_mov_b32_e32 v8, v145
	v_lshlrev_b64 v[176:177], s36, v[8:9]
	v_min_u32_e32 v8, 1, v176
	v_or_b32_e32 v8, v177, v8
	v_cvt_f32_u32_e32 v8, v8
	v_cvt_f32_u32_e32 v144, v144
	v_mul_f32_e32 v145, v191, v194
	v_ldexp_f32 v8, v8, s35
	v_fmac_f32_e32 v8, 0x2f800000, v144
	v_fmamk_f32 v8, v8, 0x3a000000, v183
	v_rsq_f32_e32 v144, v8
	v_floor_f32_e32 v8, v145
	v_mul_f32_e32 v176, v141, v144
	v_pk_mul_f32 v[128:129], v[128:129], v[176:177] op_sel_hi:[1,0]
	v_pk_mul_f32 v[126:127], v[126:127], v[176:177] op_sel_hi:[1,0]
	v_pk_mul_f32 v[124:125], v[124:125], v[176:177] op_sel_hi:[1,0]
	v_pk_mul_f32 v[122:123], v[122:123], v[176:177] op_sel_hi:[1,0]
	s_cbranch_vccz .LBB0_729
	v_fma_f32 v145, v180, v194, -v196
	v_fma_f32 v154, v181, v194, -v197
	v_cos_f32_e32 v144, v145
	v_sin_f32_e32 v178, v145
	v_cos_f32_e32 v145, v154
	v_sin_f32_e32 v179, v154
	v_fma_f32 v154, v190, v194, -v195
	v_fma_f32 v156, v191, v194, -v8
	v_cos_f32_e32 v155, v154
	v_sin_f32_e32 v154, v154
	v_cos_f32_e32 v204, v156
	v_sin_f32_e32 v205, v156
	v_pk_mul_f32 v[198:199], v[178:179], v[122:123]
	v_pk_mul_f32 v[122:123], v[144:145], v[122:123]
	v_mul_f32_e32 v202, v154, v124
	v_mul_f32_e32 v208, v155, v124
	v_mov_b32_e32 v124, v129
	v_pk_fma_f32 v[144:145], v[144:145], v[126:127], v[198:199] neg_lo:[0,0,1] neg_hi:[0,0,1]
	v_mov_b32_e32 v198, v205
	v_mov_b32_e32 v199, v204
	v_mul_f32_e32 v200, v155, v128
	v_mul_f32_e32 v206, v154, v128
	v_pk_mul_f32 v[128:129], v[204:205], v[124:125]
	v_pk_mul_f32 v[124:125], v[198:199], v[124:125]
	v_mov_b32_e32 v201, v128
	v_mov_b32_e32 v203, v129
	v_mov_b32_e32 v207, v124
	v_mov_b32_e32 v209, v125
	v_pk_add_f32 v[128:129], v[200:201], v[202:203] neg_lo:[0,1] neg_hi:[0,1]
	v_pk_fma_f32 v[122:123], v[178:179], v[126:127], v[122:123]
	v_pk_add_f32 v[124:125], v[206:207], v[208:209]
	v_mov_b32_e32 v126, v144
	v_mov_b32_e32 v127, v145

.LBB0_731:
	v_cvt_pk_bf16_f32 v176, v118, v119
	v_cvt_pk_bf16_f32 v177, v120, v121
	v_mov_b32_e32 v8, v175
	v_cvt_pk_bf16_f32 v194, v114, v115
	v_cvt_pk_bf16_f32 v195, v116, v117
	global_store_dwordx2 v[178:179], v[176:177], off offset:256
	global_store_dwordx2 v[178:179], v[194:195], off offset:288
	v_lshlrev_b64 v[176:177], s36, v[8:9]
	v_min_u32_e32 v8, 1, v176
	v_or_b32_e32 v8, v177, v8
	v_cvt_f32_u32_e32 v8, v8
	v_cvt_f32_u32_e32 v154, v174
	s_and_b64 vcc, exec, s[42:43]
	v_ldexp_f32 v8, v8, s35
	v_fmac_f32_e32 v8, 0x2f800000, v154
	v_fmamk_f32 v8, v8, 0x3a000000, v183
	v_rsq_f32_e32 v154, v8
	v_bitop3_b32 v8, v140, s2, 16 bitop3:0xc8
	v_cvt_f32_u32_e32 v8, v8
	v_mul_f32_e32 v174, v141, v154
	v_pk_mul_f32 v[112:113], v[112:113], v[174:175] op_sel_hi:[1,0]
	v_pk_mul_f32 v[154:155], v[180:181], v[8:9] op_sel_hi:[1,0]
	v_pk_mul_f32 v[156:157], v[190:191], v[8:9] op_sel_hi:[1,0]
	v_pk_mul_f32 v[110:111], v[110:111], v[174:175] op_sel_hi:[1,0]
	v_pk_mul_f32 v[108:109], v[108:109], v[174:175] op_sel_hi:[1,0]
	v_pk_mul_f32 v[106:107], v[106:107], v[174:175] op_sel_hi:[1,0]
	v_floor_f32_e32 v195, v154
	v_floor_f32_e32 v194, v155
	v_floor_f32_e32 v179, v156
	v_floor_f32_e32 v178, v157
	s_cbranch_vccnz .LBB0_733
	v_fma_f32 v154, v180, v8, -v195
	v_cos_f32_e32 v176, v154
	v_sin_f32_e32 v196, v154
	v_fma_f32 v154, v181, v8, -v194
	v_cos_f32_e32 v177, v154
	v_sin_f32_e32 v197, v154
	v_fma_f32 v154, v190, v8, -v179
	v_fma_f32 v156, v191, v8, -v178
	v_cos_f32_e32 v155, v154
	v_sin_f32_e32 v154, v154
	v_cos_f32_e32 v204, v156
	v_sin_f32_e32 v205, v156
	v_pk_mul_f32 v[198:199], v[196:197], v[106:107]
	v_pk_mul_f32 v[106:107], v[176:177], v[106:107]
	v_mul_f32_e32 v202, v154, v108
	v_mul_f32_e32 v208, v155, v108
	v_mov_b32_e32 v108, v113
	v_pk_fma_f32 v[176:177], v[176:177], v[110:111], v[198:199] neg_lo:[0,0,1] neg_hi:[0,0,1]
	v_mov_b32_e32 v198, v205
	v_mov_b32_e32 v199, v204
	v_mul_f32_e32 v200, v155, v112
	v_mul_f32_e32 v206, v154, v112
	v_pk_mul_f32 v[112:113], v[204:205], v[108:109]
	v_pk_mul_f32 v[108:109], v[198:199], v[108:109]
	v_mov_b32_e32 v201, v112
	v_mov_b32_e32 v203, v113
	v_mov_b32_e32 v207, v108
	v_mov_b32_e32 v209, v109
	v_pk_add_f32 v[112:113], v[200:201], v[202:203] neg_lo:[0,1] neg_hi:[0,1]
	v_pk_fma_f32 v[106:107], v[196:197], v[110:111], v[106:107]
	v_pk_add_f32 v[108:109], v[206:207], v[208:209]
	v_mov_b32_e32 v110, v176
	v_mov_b32_e32 v111, v177

.LBB0_735:
	v_cvt_pk_bf16_f32 v174, v102, v103
	v_cvt_pk_bf16_f32 v175, v104, v105
	v_mov_b32_e32 v8, v173
	v_cvt_pk_bf16_f32 v178, v98, v99
	v_cvt_pk_bf16_f32 v179, v100, v101
	global_store_dwordx2 v[176:177], v[174:175], off offset:256
	global_store_dwordx2 v[176:177], v[178:179], off offset:288
	v_lshlrev_b64 v[174:175], s36, v[8:9]
	v_min_u32_e32 v8, 1, v174
	v_or_b32_e32 v8, v175, v8
	v_cvt_f32_u32_e32 v8, v8
	v_cvt_f32_u32_e32 v154, v172
	s_movk_i32 s4, 0x7ef
	v_ldexp_f32 v8, v8, s35
	v_fmac_f32_e32 v8, 0x2f800000, v154
	v_fmamk_f32 v8, v8, 0x3a000000, v183
	v_rsq_f32_e32 v154, v8
	v_bitop3_b32 v8, v140, s4, 32 bitop3:0xc8
	v_cvt_f32_u32_e32 v8, v8
	s_and_b64 vcc, exec, s[42:43]
	v_mul_f32_e32 v172, v141, v154
	v_pk_mul_f32 v[96:97], v[96:97], v[172:173] op_sel_hi:[1,0]
	v_pk_mul_f32 v[154:155], v[180:181], v[8:9] op_sel_hi:[1,0]
	v_pk_mul_f32 v[156:157], v[190:191], v[8:9] op_sel_hi:[1,0]
	v_pk_mul_f32 v[94:95], v[94:95], v[172:173] op_sel_hi:[1,0]
	v_pk_mul_f32 v[92:93], v[92:93], v[172:173] op_sel_hi:[1,0]
	v_pk_mul_f32 v[90:91], v[90:91], v[172:173] op_sel_hi:[1,0]
	v_floor_f32_e32 v179, v154
	v_floor_f32_e32 v178, v155
	v_floor_f32_e32 v177, v156
	v_floor_f32_e32 v176, v157
	s_cbranch_vccnz .LBB0_737
	v_fma_f32 v154, v180, v8, -v179
	v_cos_f32_e32 v174, v154
	v_sin_f32_e32 v194, v154
	v_fma_f32 v154, v181, v8, -v178
	v_cos_f32_e32 v175, v154
	v_sin_f32_e32 v195, v154
	v_fma_f32 v154, v190, v8, -v177
	v_fma_f32 v156, v191, v8, -v176
	v_cos_f32_e32 v155, v154
	v_sin_f32_e32 v154, v154
	v_cos_f32_e32 v202, v156
	v_sin_f32_e32 v203, v156
	v_pk_mul_f32 v[196:197], v[194:195], v[90:91]
	v_pk_mul_f32 v[90:91], v[174:175], v[90:91]
	v_mul_f32_e32 v200, v154, v92
	v_mul_f32_e32 v206, v155, v92
	v_mov_b32_e32 v92, v97
	v_pk_fma_f32 v[174:175], v[174:175], v[94:95], v[196:197] neg_lo:[0,0,1] neg_hi:[0,0,1]
	v_mov_b32_e32 v196, v203
	v_mov_b32_e32 v197, v202
	v_mul_f32_e32 v198, v155, v96
	v_mul_f32_e32 v204, v154, v96
	v_pk_mul_f32 v[96:97], v[202:203], v[92:93]
	v_pk_mul_f32 v[92:93], v[196:197], v[92:93]
	v_mov_b32_e32 v199, v96
	v_mov_b32_e32 v201, v97
	v_mov_b32_e32 v205, v92
	v_mov_b32_e32 v207, v93
	v_pk_add_f32 v[96:97], v[198:199], v[200:201] neg_lo:[0,1] neg_hi:[0,1]
	v_pk_fma_f32 v[90:91], v[194:195], v[94:95], v[90:91]
	v_pk_add_f32 v[92:93], v[204:205], v[206:207]
	v_mov_b32_e32 v94, v174
	v_mov_b32_e32 v95, v175

.LBB0_743:
	v_cvt_pk_bf16_f32 v174, v70, v71
	v_cvt_pk_bf16_f32 v175, v72, v73
	v_mov_b32_e32 v8, v151
	v_cvt_pk_bf16_f32 v176, v66, v67
	v_cvt_pk_bf16_f32 v177, v68, v69
	global_store_dwordx2 v[172:173], v[174:175], off offset:256
	global_store_dwordx2 v[172:173], v[176:177], off offset:288
	v_lshlrev_b64 v[172:173], s36, v[8:9]
	v_min_u32_e32 v8, 1, v172
	v_or_b32_e32 v8, v173, v8
	v_cvt_f32_u32_e32 v8, v8
	v_cvt_f32_u32_e32 v150, v150
	v_add_u32_e32 v152, 0x80, v140
	v_ldexp_f32 v8, v8, s35
	v_fmac_f32_e32 v8, 0x2f800000, v150
	v_fmamk_f32 v8, v8, 0x3a000000, v183
	v_rsq_f32_e32 v150, v8
	v_and_b32_e32 v8, 0x7cf, v152
	v_cvt_f32_u32_e32 v8, v8
	s_and_b64 vcc, exec, s[42:43]
	v_mul_f32_e32 v150, v141, v150
	v_pk_mul_f32 v[64:65], v[64:65], v[150:151] op_sel_hi:[1,0]
	v_pk_mul_f32 v[62:63], v[62:63], v[150:151] op_sel_hi:[1,0]
	v_pk_mul_f32 v[60:61], v[60:61], v[150:151] op_sel_hi:[1,0]
	v_pk_mul_f32 v[58:59], v[58:59], v[150:151] op_sel_hi:[1,0]
	v_mul_f32_e32 v151, v180, v8
	v_mul_f32_e32 v153, v181, v8
	v_pk_mul_f32 v[154:155], v[190:191], v[8:9] op_sel_hi:[1,0]
	v_floor_f32_e32 v175, v151
	v_floor_f32_e32 v174, v153
	v_floor_f32_e32 v173, v154
	v_floor_f32_e32 v172, v155
	s_cbranch_vccnz .LBB0_745
	v_fma_f32 v151, v180, v8, -v175
	v_cos_f32_e32 v176, v151
	v_sin_f32_e32 v178, v151
	v_fma_f32 v151, v181, v8, -v174
	v_cos_f32_e32 v177, v151
	v_sin_f32_e32 v179, v151
	v_fma_f32 v151, v190, v8, -v173
	v_fma_f32 v154, v191, v8, -v172
	v_cos_f32_e32 v153, v151
	v_sin_f32_e32 v151, v151
	v_cos_f32_e32 v200, v154
	v_sin_f32_e32 v201, v154
	v_pk_mul_f32 v[194:195], v[178:179], v[58:59]
	v_pk_mul_f32 v[58:59], v[176:177], v[58:59]
	v_mul_f32_e32 v198, v151, v60
	v_mul_f32_e32 v204, v153, v60
	v_mov_b32_e32 v60, v65
	v_pk_fma_f32 v[176:177], v[176:177], v[62:63], v[194:195] neg_lo:[0,0,1] neg_hi:[0,0,1]
	v_mov_b32_e32 v194, v201
	v_mov_b32_e32 v195, v200
	v_mul_f32_e32 v196, v153, v64
	v_mul_f32_e32 v202, v151, v64
	v_pk_mul_f32 v[64:65], v[200:201], v[60:61]
	v_pk_mul_f32 v[60:61], v[194:195], v[60:61]
	v_mov_b32_e32 v197, v64
	v_mov_b32_e32 v199, v65
	v_mov_b32_e32 v203, v60
	v_mov_b32_e32 v205, v61
	v_pk_add_f32 v[64:65], v[196:197], v[198:199] neg_lo:[0,1] neg_hi:[0,1]
	v_pk_fma_f32 v[58:59], v[178:179], v[62:63], v[58:59]
	v_pk_add_f32 v[60:61], v[202:203], v[204:205]
	v_mov_b32_e32 v62, v176
	v_mov_b32_e32 v63, v177
